# P2: odd workgroups run their four mixer-B units first and the mixer-A unit last (A and B work overlap across the chip)
# speedup vs baseline: 1.0099x; 1.0099x over previous
; __global__ void __launch_bounds__(512, 2) fwd_kernel(Args A) {
;     ...
;             for (int u = bx; u < 256 + 1024; u += G) {
;                 if (u < 256) attnA_unit(lds, A, u);
;                 if (u >= 256) {
;                     int ub = u - 256;
;                     if (G == 256) {
;                         const int k = ub >> 8, xcd = bx & 7, j = (bx >> 3) * 4 + k;
;                         ub = (xcd >> 1) * 256 + ((xcd & 1) * 4 + (j >> 5)) * 32 + (j & 31); }
;                     attnB_unit(lds, A, ub, A.kng + l * 64);
;                 }
.LBB0_272:
	s_andn2_b64 vcc, exec, s[4:5]
	s_cbranch_vccnz .LBB0_360
	v_readlane_b32 s4, v254, 44
	v_readlane_b32 s5, v254, 45
	s_andn2_b64 vcc, exec, s[4:5]
	s_cbranch_vccnz .LBB0_328
	v_readlane_b32 s4, v255, 44
	v_readlane_b32 s5, v255, 45
	s_lshl_b32 s60, s4, 6
	s_lshl_b64 s[4:5], s[60:61], 2
	s_add_u32 s4, s56, s4
	s_addc_u32 s5, s57, s5
	v_writelane_b32 v255, s4, 48
	s_mov_b32 s69, s2
	s_mov_b32 s70, s2
	s_bitcmp1_b32 s2, 0
	s_cbranch_scc0 .Lp2_even
	s_add_i32 s69, s69, s26
	s_add_i32 s70, s70, s26
.Lp2_even:
	v_writelane_b32 v255, s5, 49
	s_branch .LBB0_277

; __global__ void __launch_bounds__(512, 2) fwd_kernel(Args A) {
;     ...
;             for (int u = bx; u < 256 + 1024; u += G) {
;                 if (u < 256) attnA_unit(lds, A, u);
;                 if (u >= 256) {
;                     int ub = u - 256;
;                     if (G == 256) {
;                         const int k = ub >> 8, xcd = bx & 7, j = (bx >> 3) * 4 + k;
;                         ub = (xcd >> 1) * 256 + ((xcd & 1) * 4 + (j >> 5)) * 32 + (j & 31); }
;                     attnB_unit(lds, A, ub, A.kng + l * 64);
;                 }
;  }
.LBB0_276:
	s_bitcmp1_b32 s2, 0
	s_cbranch_scc0 .Lp2_276
	s_cmpk_lt_i32 s70, 0x100
	s_cbranch_scc1 .LBB0_328
	s_add_i32 s70, s70, s26
	s_add_i32 s69, s69, s26
	s_cmpk_gt_i32 s70, 0x4ff
	s_cbranch_scc0 .LBB0_277
	s_mov_b32 s69, s2
	s_mov_b32 s70, s2
	s_branch .LBB0_277
